# up-GEMM epilogue: first column half's conv operands also LDS-DMA prefetched at epilogue start (covered by the row-scale wait), on top of the second-half prefetch
# speedup vs baseline: 1.0044x; 1.0044x over previous
; __device__ __forceinline__ void load_row_scales(const float* ssp, int row0, int fq, float (&rs)[2][4]) {
;     f32x4 part[2][4];
;     const float* sp = ssp + (size_t)row0 * 16 + 4 * fq;
; #pragma unroll
;     for (int ai = 0; ai < 2; ++ai)
; #pragma unroll
;         for (int m = 0; m < 4; ++m) part[ai][m] = *(const f32x4*)(sp + (size_t)(ai * HALF + m * 16) * 16);
; #pragma unroll
;     for (int ai = 0; ai < 2; ++ai)
; #pragma unroll
;         for (int m = 0; m < 4; ++m) { float t = (part[ai][m][0] + part[ai][m][1]) + (part[ai][m][2] + part[ai][m][3]);
;             t += __shfl_xor(t, 16); t += __shfl_xor(t, 32);
;             rs[ai][m] = 1.0f / sqrtf(t * (1.0f / 1024.0f) + 1e-6f); }
;     __device__ __forceinline__ void operator()(f32x4 (&acc)[2][2][4][2], const Unit& u, int wr, int wc, int fr, int fq) const {
;     ...
;         for (int n = 0; n < 2; ++n) {
;             const int gc0 = u.pn * 128 + wc * 32 + 8 * fq + 4 * n;
;             const float* cwp = cw + gc0; asm volatile("" : "+v"(cwp));
;             const f32x4 wg0 = *(const f32x4*)(cwp), wg1 = *(const f32x4*)(cwp + FF2c), wg2 = *(const f32x4*)(cwp + 2 * FF2c);
;             const f32x4 wv0 = *(const f32x4*)(cwp + FFc), wv1 = *(const f32x4*)(cwp + FF2c + FFc), wv2 = *(const f32x4*)(cwp + 2 * FF2c + FFc);
;             const f32x4 bg = *(const f32x4*)(cb + gc0), bv = *(const f32x4*)(cb + FFc + gc0);
.LBB0_1350:
	s_lshl_b32 s13, s13, 8
	s_add_i32 s13, s13, s24
	v_or_b32_e32 v176, s13, v161
	v_ashrrev_i32_e32 v177, 31, v176
	v_lshlrev_b64 v[130:131], 6, v[176:177]
	v_lshl_add_u64 v[146:147], v[162:163], 0, v[130:131]
	global_load_dwordx4 v[130:133], v[146:147], off
	global_load_dwordx4 v[134:137], v[146:147], off offset:1024
	global_load_dwordx4 v[138:141], v[146:147], off offset:2048
	global_load_dwordx4 v[142:145], v[146:147], off offset:3072
	v_add_co_u32_e32 v168, vcc, 0x2000, v146
	v_mov_b32_e32 v177, v1
	s_nop 0
	v_addc_co_u32_e32 v169, vcc, 0, v147, vcc
	global_load_dwordx4 v[146:149], v[168:169], off
	global_load_dwordx4 v[150:153], v[168:169], off offset:1024
	global_load_dwordx4 v[170:173], v[168:169], off offset:2048
	global_load_dwordx4 v[178:181], v[168:169], off offset:3072
	v_mbcnt_lo_u32_b32 v231, -1, 0
	v_mbcnt_hi_u32_b32 v231, -1, v231
	v_lshrrev_b32_e32 v231, 4, v231
	v_lshl_add_u32 v231, v231, 8, s96
	v_add_u32_e32 v231, 0x20000, v231
	s_mov_b32 exec_lo, 0x10001
	s_mov_b32 exec_hi, 0x10001
	s_nop 1
	v_lshl_or_b32 v224, s12, 7, v238
	v_mov_b32_e32 v223, 0
	v_ashrrev_i32_e32 v225, 31, v224
	s_add_i32 m0, s96, 0x22000
	v_lshlrev_b64 v[224:225], 2, v[224:225]
	v_lshl_add_u64 v[220:221], s[70:71], 0, v[224:225]
	global_load_lds_dwordx4 v[220:221], off
	v_mov_b32_e32 v222, 0x5800
	s_add_i32 m0, s96, 0x22010
	v_lshl_add_u64 v[226:227], v[220:221], 0, v[222:223]
	global_load_lds_dwordx4 v[226:227], off
	v_mov_b32_e32 v222, 0x2c00
	s_add_i32 m0, s96, 0x22020
	v_lshl_add_u64 v[226:227], v[220:221], 0, v[222:223]
	global_load_lds_dwordx4 v[226:227], off
	v_mov_b32_e32 v222, 0xb000
	s_add_i32 m0, s96, 0x22030
	v_lshl_add_u64 v[226:227], v[220:221], 0, v[222:223]
	global_load_lds_dwordx4 v[226:227], off
	v_mov_b32_e32 v222, 0x8400
	s_add_i32 m0, s96, 0x22040
	v_lshl_add_u64 v[226:227], v[220:221], 0, v[222:223]
	global_load_lds_dwordx4 v[226:227], off
	v_mov_b32_e32 v222, 0xdc00
	s_add_i32 m0, s96, 0x22050
	v_lshl_add_u64 v[226:227], v[220:221], 0, v[222:223]
	global_load_lds_dwordx4 v[226:227], off
	s_add_i32 m0, s96, 0x22060
	v_lshl_add_u64 v[226:227], s[72:73], 0, v[224:225]
	global_load_lds_dwordx4 v[226:227], off
	s_add_i32 m0, s96, 0x22070
	v_lshl_add_u64 v[226:227], s[76:77], 0, v[224:225]
	global_load_lds_dwordx4 v[226:227], off
	s_mov_b64 exec, -1
	s_nop 1
	v_and_b32_e32 v169, 64, v229
	v_xor_b32_e32 v168, 16, v229
	v_add_u32_e32 v169, 64, v169
	v_cmp_lt_i32_e32 vcc, v168, v169
	v_mov_b32_dpp v177, v177 row_ror:1 row_mask:0xf bank_mask:0xf
	v_mov_b32_e32 v189, v177
	v_cndmask_b32_e32 v168, v229, v168, vcc
	v_lshlrev_b32_e32 v174, 2, v168
	v_xor_b32_e32 v168, 32, v229
	v_cmp_lt_i32_e32 vcc, v168, v169
	s_waitcnt vmcnt(0)
	s_mov_b32 s100, 1
	v_mov_b32_e32 v169, v132
	v_cndmask_b32_e32 v168, v229, v168, vcc
	v_lshlrev_b32_e32 v175, 2, v168
	v_mov_b32_e32 v168, v131
	v_mov_b32_e32 v131, v133
	v_pk_add_f32 v[130:131], v[168:169], v[130:131]
	s_nop 0
	v_add_f32_e32 v130, v130, v131
	v_mov_b32_e32 v131, v130
	s_nop 1
	v_permlane16_swap_b32_e32 v131, v130
	s_waitcnt lgkmcnt(0)
	v_add_f32_e32 v130, v130, v131
	v_mov_b32_e32 v131, v130
	s_nop 1
	v_permlane32_swap_b32_e32 v131, v130
	s_waitcnt lgkmcnt(0)
	v_add_f32_e32 v130, v130, v131
	v_fmamk_f32 v130, v130, 0x3a800000, v230
	s_ashr_i32 s0, s13, 5
	v_rsq_f32_e32 v168, v130
	s_nop 0
	v_mov_b32_e32 v130, v135
	v_mov_b32_e32 v131, v136
	v_mov_b32_e32 v135, v137
	v_pk_add_f32 v[130:131], v[130:131], v[134:135]
	s_nop 0
	v_add_f32_e32 v130, v130, v131
	v_mov_b32_e32 v131, v130
	s_nop 1
	v_permlane16_swap_b32_e32 v131, v130
	s_waitcnt lgkmcnt(0)
	v_add_f32_e32 v205, v130, v131
	v_mov_b32_e32 v130, v139
	v_mov_b32_e32 v131, v140
	v_mov_b32_e32 v139, v141
	v_pk_add_f32 v[130:131], v[130:131], v[138:139]
	ds_bpermute_b32 v206, v175, v205
	v_add_f32_e32 v130, v130, v131
	v_mov_b32_e32 v131, v130
	s_nop 1
	v_permlane16_swap_b32_e32 v131, v130
	s_waitcnt lgkmcnt(0)
	v_add_f32_e32 v203, v130, v131
	v_mov_b32_e32 v130, v143
	v_mov_b32_e32 v131, v144
	v_mov_b32_e32 v143, v145
	v_pk_add_f32 v[130:131], v[130:131], v[142:143]
	ds_bpermute_b32 v204, v175, v203
	v_add_f32_e32 v130, v130, v131
	v_mov_b32_e32 v131, v130
	s_nop 1
	v_permlane16_swap_b32_e32 v131, v130
	s_waitcnt lgkmcnt(0)
	v_add_f32_e32 v182, v130, v131
	v_mov_b32_e32 v130, v147
	v_mov_b32_e32 v131, v148
	v_mov_b32_e32 v147, v149
	v_pk_add_f32 v[130:131], v[130:131], v[146:147]
	ds_bpermute_b32 v202, v175, v182
	v_add_f32_e32 v130, v130, v131
	v_mov_b32_e32 v131, v130
	s_nop 1
	v_permlane16_swap_b32_e32 v131, v130
	s_waitcnt lgkmcnt(0)
	v_add_f32_e32 v244, v130, v131
	v_mov_b32_e32 v130, v151
	v_mov_b32_e32 v131, v152
	v_mov_b32_e32 v151, v153
	v_pk_add_f32 v[130:131], v[130:131], v[150:151]
	ds_bpermute_b32 v245, v175, v244
	v_add_f32_e32 v130, v130, v131
	v_mov_b32_e32 v131, v130
	s_nop 1
	v_permlane16_swap_b32_e32 v131, v130
	s_waitcnt lgkmcnt(0)
	v_add_f32_e32 v242, v130, v131
	v_mov_b32_e32 v130, v171
	v_mov_b32_e32 v131, v172
	v_mov_b32_e32 v171, v173
	v_pk_add_f32 v[130:131], v[130:131], v[170:171]
	v_lshl_or_b32 v170, s12, 7, v238
	v_add_f32_e32 v130, v130, v131
	v_mov_b32_e32 v131, v130
	s_nop 1
	v_permlane16_swap_b32_e32 v131, v130
	v_ashrrev_i32_e32 v171, 31, v170
	v_lshlrev_b64 v[150:151], 2, v[170:171]
	v_lshl_add_u64 v[172:173], s[70:71], 0, v[150:151]
	ds_bpermute_b32 v243, v175, v242
	s_waitcnt lgkmcnt(0)
	v_add_f32_e32 v240, v130, v131
	v_mov_b32_e32 v130, v179
	v_mov_b32_e32 v131, v180
	v_mov_b32_e32 v179, v181
	v_pk_add_f32 v[130:131], v[130:131], v[178:179]
	ds_bpermute_b32 v241, v175, v240
	v_add_f32_e32 v130, v130, v131
	v_mov_b32_e32 v131, v130
	s_nop 1
	v_permlane16_swap_b32_e32 v131, v130
	v_lshlrev_b64 v[178:179], 1, v[170:171]
	s_waitcnt lgkmcnt(0)
;     __device__ __forceinline__ void operator()(f32x4 (&acc)[2][2][4][2], const Unit& u, int wr, int wc, int fr, int fq) const {
;     ...
;         for (int n = 0; n < 2; ++n) {
;             const int gc0 = u.pn * 128 + wc * 32 + 8 * fq + 4 * n;
;             const float* cwp = cw + gc0; asm volatile("" : "+v"(cwp));
;             const f32x4 wg0 = *(const f32x4*)(cwp), wg1 = *(const f32x4*)(cwp + FF2c), wg2 = *(const f32x4*)(cwp + 2 * FF2c);
;             const f32x4 wv0 = *(const f32x4*)(cwp + FFc), wv1 = *(const f32x4*)(cwp + FF2c + FFc), wv2 = *(const f32x4*)(cwp + 2 * FF2c + FFc);
;             const f32x4 bg = *(const f32x4*)(cb + gc0), bv = *(const f32x4*)(cb + FFc + gc0);
;             bf16_t* gp = G + (size_t)row0 * FFc + gc0;
;             bf16_t* sb = Fb + ((size_t)(row0 >> 6) * 2 + (fr & 1)) * FF2c + gc0;
;             bf16_t* hb = Hb + ((size_t)(row0 >> 6) * 2 + (fr & 1)) * FF2c + gc0;
; #pragma unroll
;             for (int ai = 0; ai < 2; ++ai) {
; #pragma unroll
;                 for (int m = 0; m < 4; ++m) {
;                     float og[4];
; #pragma unroll
;                     for (int j = 0; j < 4; ++j) {
;                         const float vg = acc[ai][0][m][n][j], vv = acc[ai][1][m][n][j];
;                         const float pg = (m > 0) ? acc[ai][0][m - 1][n][j] : 0.f, pv = (m > 0) ? acc[ai][1][m - 1][n][j] : 0.f;
;                         const float g1 = dppf(dppf(0.f, pg, 2), vg, 0), g2 = dppf(dppf(0.f, pg, 3), vg, 1);
;                         const float v1 = dppf(dppf(0.f, pv, 2), vv, 0), v2 = dppf(dppf(0.f, pv, 3), vv, 1);
;                         const float cgate = bg[j] + wg0[j] * g2 + wg1[j] * g1 + wg2[j] * vg;
;                         const float cval = bv[j] + wv0[j] * v2 + wv1[j] * v1 + wv2[j] * vv;
;                         og[j] = cgate * __builtin_amdgcn_rcpf(1.0f + __builtin_amdgcn_exp2f(-1.4426950408889634f * cgate)) * cval; }
;                     const unsigned long long w = (unsigned long long)cvt_pk_bf16(og[0], og[1]) | ((unsigned long long)cvt_pk_bf16(og[2], og[3]) << 32);
;                     if (m == 0) {
;                         if (fr >= 2) *(unsigned long long*)gp = w;
;                         else { *(unsigned long long*)sb = (unsigned long long)cvt_pk_bf16(acc[ai][0][0][n][0], acc[ai][0][0][n][1]) | ((unsigned long long)cvt_pk_bf16(acc[ai][0][0][n][2], acc[ai][0][0][n][3]) << 32);
	v_add_f32_e32 v169, v130, v131
	v_pk_mul_f32 v[196:197], v[98:99], v[168:169] op_sel_hi:[1,0]
	v_or_b32_e32 v98, s0, v160
	v_mad_i64_i32 v[200:201], s[0:1], v98, s37, 0
	v_pk_mul_f32 v[198:199], v[102:103], v[168:169] op_sel_hi:[1,0]
	v_mov_b64_e32 v[102:103], v[172:173]
	s_movk_i32 s0, 0x5000
	ds_bpermute_b32 v183, v175, v169
	v_add_co_u32_e32 v98, vcc, s0, v102
	s_mov_b32 s0, 0xb000
	s_nop 0
	v_addc_co_u32_e32 v99, vcc, 0, v103, vcc
	ds_read_b128 v[142:145], v231 offset:8208
	v_add_co_u32_e32 v98, vcc, s0, v102
	s_movk_i32 s0, 0x2000
	s_nop 0
	v_addc_co_u32_e32 v99, vcc, 0, v103, vcc
	v_pk_mul_f32 v[194:195], v[104:105], v[168:169] op_sel_hi:[1,0]
	v_add_co_u32_e32 v104, vcc, s0, v102
	v_lshl_add_u64 v[174:175], s[72:73], 0, v[150:151]
	ds_read_b128 v[138:141], v231 offset:8192
	v_addc_co_u32_e32 v105, vcc, 0, v103, vcc
	s_mov_b32 s0, 0x8000
	ds_read_b128 v[146:149], v231 offset:8288
	ds_read_b128 v[130:133], v231 offset:8224
	v_add_co_u32_e32 v104, vcc, s0, v102
	v_lshl_add_u64 v[150:151], s[76:77], 0, v[150:151]
	v_pk_mul_f32 v[192:193], v[100:101], v[168:169] op_sel_hi:[1,0]
	ds_read_b128 v[98:101], v231 offset:8240
	v_addc_co_u32_e32 v105, vcc, 0, v103, vcc
	ds_read_b128 v[150:153], v231 offset:8304
	s_mov_b32 s0, 0xd000
	ds_read_b128 v[134:137], v231 offset:8256
	v_add_co_u32_e32 v102, vcc, s0, v102
	v_readlane_b32 s0, v253, 44
	s_nop 0
	v_addc_co_u32_e32 v103, vcc, 0, v103, vcc
	ds_read_b128 v[102:105], v231 offset:8272
	v_readlane_b32 s1, v253, 45
	v_mov_b32_dpp v189, v196 row_shr:1 row_mask:0xf bank_mask:0xf
	s_nop 0
	v_lshl_add_u64 v[180:181], v[200:201], 1, s[0:1]
	v_lshl_add_u64 v[184:185], v[180:181], 0, v[178:179]
	v_mov_b32_e32 v181, v1
	v_mov_b32_e32 v180, v177
	s_nop 0
	v_mov_b32_dpp v181, v181 row_ror:2 row_mask:0xf bank_mask:0xf
	v_mov_b32_e32 v188, v181
	v_mov_b32_dpp v180, v198 row_shr:1 row_mask:0xf bank_mask:0xf
	v_mov_b32_e32 v190, v181
	v_mov_b32_dpp v188, v198 row_shr:2 row_mask:0xf bank_mask:0xf
	v_mov_b32_e32 v191, v181
	v_mov_b32_dpp v190, v196 row_shr:2 row_mask:0xf bank_mask:0xf
	v_mov_b32_e32 v207, v181
	v_mov_b32_dpp v191, v197 row_shr:2 row_mask:0xf bank_mask:0xf
	s_waitcnt vmcnt(0) lgkmcnt(0)
	v_mbcnt_lo_u32_b32 v231, -1, 0
	v_mbcnt_hi_u32_b32 v231, -1, v231
	v_lshrrev_b32_e32 v231, 4, v231
	v_lshl_add_u32 v231, v231, 8, s96
	v_add_u32_e32 v231, 0x20000, v231
	s_mov_b32 exec_lo, 0x10001
	s_mov_b32 exec_hi, 0x10001
	s_nop 1
	v_lshl_add_u64 v[220:221], v[172:173], 0, 16
	v_mov_b32_e32 v223, 0
	s_add_i32 m0, s96, 0x20000
	s_nop 0
	global_load_lds_dwordx4 v[220:221], off
	v_mov_b32_e32 v222, 0x5800
	s_add_i32 m0, s96, 0x20010
	v_lshl_add_u64 v[226:227], v[220:221], 0, v[222:223]
	global_load_lds_dwordx4 v[226:227], off
	v_mov_b32_e32 v222, 0xb000
	s_add_i32 m0, s96, 0x20020
	v_lshl_add_u64 v[224:225], v[220:221], 0, v[222:223]
	global_load_lds_dwordx4 v[224:225], off
	v_mov_b32_e32 v222, 0x2c00
	s_add_i32 m0, s96, 0x20030
	v_lshl_add_u64 v[226:227], v[220:221], 0, v[222:223]
	global_load_lds_dwordx4 v[226:227], off
	v_mov_b32_e32 v222, 0x8400
	s_add_i32 m0, s96, 0x20040
	v_lshl_add_u64 v[224:225], v[220:221], 0, v[222:223]
	global_load_lds_dwordx4 v[224:225], off
	v_mov_b32_e32 v222, 0xdc00
	s_add_i32 m0, s96, 0x20050
	v_lshl_add_u64 v[226:227], v[220:221], 0, v[222:223]
	global_load_lds_dwordx4 v[226:227], off
	s_add_i32 m0, s96, 0x20060
	v_lshl_add_u64 v[224:225], v[174:175], 0, 16
	global_load_lds_dwordx4 v[224:225], off
	v_or_b32_e32 v226, 4, v170
	s_add_i32 m0, s96, 0x20070
	v_ashrrev_i32_e32 v227, 31, v226
	v_lshl_add_u64 v[226:227], v[226:227], 2, s[76:77]
	global_load_lds_dwordx4 v[226:227], off
	s_mov_b64 exec, -1
	s_nop 1
	v_fma_f32 v188, v138, v188, v146
	v_fmac_f32_e32 v188, v142, v180
	v_mov_b32_dpp v207, v192 row_shr:2 row_mask:0xf bank_mask:0xf
	v_fmac_f32_e32 v188, v198, v98
	v_fma_f32 v180, v130, v190, v150
	v_mov_b32_e32 v190, v177
	v_fmac_f32_e32 v180, v134, v189
	v_mul_f32_e32 v189, 0xbfb8aa3b, v188
	v_exp_f32_e32 v189, v189
	v_mov_b32_dpp v190, v197 row_shr:1 row_mask:0xf bank_mask:0xf
	v_add_f32_e32 v189, 1.0, v189
	v_rcp_f32_e32 v189, v189
	v_fmac_f32_e32 v180, v196, v102
	v_mul_f32_e32 v188, v188, v189
	v_mov_b32_e32 v189, v181
	v_mul_f32_e32 v180, v180, v188
	v_mov_b32_e32 v188, v177
	v_mov_b32_dpp v189, v199 row_shr:2 row_mask:0xf bank_mask:0xf
	v_fma_f32 v189, v139, v189, v147
	v_mov_b32_dpp v188, v199 row_shr:1 row_mask:0xf bank_mask:0xf
	v_fmac_f32_e32 v189, v143, v188
	v_fmac_f32_e32 v189, v199, v99
	v_fma_f32 v188, v131, v191, v151
	v_fmac_f32_e32 v188, v135, v190
	v_mul_f32_e32 v190, 0xbfb8aa3b, v189
	v_exp_f32_e32 v190, v190
	v_fmac_f32_e32 v188, v197, v103
	v_mov_b32_e32 v191, v177
	v_add_f32_e32 v190, 1.0, v190
	v_rcp_f32_e32 v190, v190
	v_mov_b32_dpp v191, v192 row_shr:1 row_mask:0xf bank_mask:0xf
	v_mul_f32_e32 v189, v189, v190
	v_mov_b32_e32 v190, v181
	v_mul_f32_e32 v188, v188, v189
	v_mov_b32_e32 v189, v177
	v_mov_b32_dpp v190, v194 row_shr:2 row_mask:0xf bank_mask:0xf
	v_fma_f32 v190, v140, v190, v148
	v_mov_b32_dpp v189, v194 row_shr:1 row_mask:0xf bank_mask:0xf
	v_fmac_f32_e32 v190, v144, v189
	v_fmac_f32_e32 v190, v194, v100
	v_fma_f32 v189, v132, v207, v152
	v_fmac_f32_e32 v189, v136, v191
	v_mul_f32_e32 v191, 0xbfb8aa3b, v190
	v_exp_f32_e32 v191, v191
	v_fmac_f32_e32 v189, v192, v104
	v_cvt_pk_bf16_f32 v180, v180, v188
	v_add_f32_e32 v191, 1.0, v191
	v_rcp_f32_e32 v191, v191
	s_nop 0
	v_mul_f32_e32 v190, v190, v191
	v_mov_b32_e32 v191, v181
	v_mul_f32_e32 v189, v189, v190
	v_mov_b32_e32 v190, v177
	v_mov_b32_dpp v191, v195 row_shr:2 row_mask:0xf bank_mask:0xf
	v_fma_f32 v191, v141, v191, v149
	v_mov_b32_dpp v190, v195 row_shr:1 row_mask:0xf bank_mask:0xf
	v_mov_b32_dpp v181, v193 row_shr:2 row_mask:0xf bank_mask:0xf
	v_fmac_f32_e32 v191, v145, v190
	v_mov_b32_dpp v177, v193 row_shr:1 row_mask:0xf bank_mask:0xf
	v_fmac_f32_e32 v191, v195, v101
	v_fma_f32 v181, v133, v181, v153
	v_fmac_f32_e32 v181, v137, v177
	v_mul_f32_e32 v177, 0xbfb8aa3b, v191
	v_exp_f32_e32 v177, v177
	v_fmac_f32_e32 v181, v193, v105
	v_add_f32_e32 v177, 1.0, v177
	v_rcp_f32_e32 v177, v177
	s_nop 0
	v_mul_f32_e32 v177, v191, v177
	v_mul_f32_e32 v177, v181, v177
	v_cvt_pk_bf16_f32 v181, v189, v177
	s_and_saveexec_b64 s[0:1], s[6:7]
	s_xor_b64 s[0:1], exec, s[0:1]
	s_mov_b64 s[50:51], 0x16000
	s_mov_b64 s[52:53], 0x58000
	s_mov_b64 s[54:55], 0xb000
	s_cbranch_execz .LBB0_1352
	v_cvt_pk_bf16_f32 v180, v198, v199
	v_cvt_pk_bf16_f32 v181, v194, v195
	v_add_co_u32_e32 v188, vcc, 0x1000, v184
	global_store_dwordx2 v[184:185], v[180:181], off
	v_cvt_pk_bf16_f32 v180, v196, v197
	v_cvt_pk_bf16_f32 v181, v192, v193
	s_nop 0
	v_addc_co_u32_e32 v189, vcc, 0, v185, vcc
	global_store_dwordx2 v[188:189], v[180:181], off offset:1536
